# non-temporal hint also on the loads of the latent-norm phase
# speedup vs baseline: 1.2121x; 1.0262x over previous
.LBB0_734:
	v_add_u32_e32 v78, s35, v25
	s_movk_i32 s0, 0x3fff
	v_cmp_lt_i32_e64 s[14:15], s0, v78
	s_and_saveexec_b64 s[0:1], s[14:15]
	s_xor_b64 s[0:1], exec, s[0:1]
	s_cbranch_execz .LBB0_738
	v_add_u32_e32 v0, 0xffffc000, v78
	v_lshrrev_b32_e32 v0, 8, v0
	v_and_b32_e32 v0, 0xfffffe, v0
	v_readlane_b32 s8, v255, 47
	v_mov_b32_e32 v1, v4
	v_readlane_b32 s9, v255, 48
	v_or_b32_e32 v0, s8, v0
	v_lshlrev_b64 v[2:3], 9, v[0:1]
	s_movk_i32 s8, 0x1ff
	v_and_or_b32 v2, v78, s8, v2
	v_lshlrev_b64 v[0:1], 9, v[2:3]
	v_lshl_add_u64 v[0:1], v[40:41], 0, v[0:1]
	global_load_dwordx2 v[84:85], v[0:1], off nt
	v_mov_b32_e32 v0, 0
	s_and_saveexec_b64 s[8:9], s[4:5]
	s_cbranch_execz .LBB0_737
	v_lshlrev_b64 v[0:1], 7, v[2:3]
	v_lshl_add_u64 v[0:1], v[42:43], 0, v[0:1]
	global_load_dword v0, v[0:1], off nt

.LBB0_738:
	s_or_saveexec_b64 s[0:1], s[0:1]
	v_mov_b32_e32 v89, 0
	v_mov_b32_e32 v20, s69
	v_mov_b32_e32 v88, 0
	v_mov_b32_e32 v87, 0
	v_mov_b32_e32 v86, v89
	v_mov_b32_e32 v79, 0
	s_xor_b64 exec, exec, s[0:1]
	s_cbranch_execz .LBB0_744
	s_waitcnt vmcnt(0)
	v_lshl_add_u64 v[0:1], s[26:27], 0, v[52:53]
	global_load_dwordx2 v[2:3], v[0:1], off nt
	v_lshl_add_u64 v[0:1], s[26:27], 0, v[50:51]
	global_load_dword v1, v[0:1], off nt
	v_mov_b32_e32 v79, 0
	v_mov_b32_e32 v0, 0
	s_and_saveexec_b64 s[8:9], s[4:5]
	s_cbranch_execz .LBB0_741
	v_lshl_add_u64 v[6:7], s[26:27], 0, v[54:55]
	global_load_ushort v0, v[6:7], off nt
	s_waitcnt vmcnt(0)
	v_lshlrev_b32_e32 v0, 16, v0
.LBB0_741:
	s_or_b64 exec, exec, s[8:9]
	v_cmp_lt_i32_e32 vcc, s89, v78
	s_and_b64 s[10:11], s[4:5], vcc
	s_and_saveexec_b64 s[8:9], s[10:11]
	s_cbranch_execz .LBB0_743
	s_mov_b32 s10, 0x1ffe0
	v_and_or_b32 v5, v90, s10, v24
	v_readlane_b32 s10, v253, 31
	v_lshlrev_b32_e32 v6, 2, v5
	v_mov_b32_e32 v7, v4
	v_readlane_b32 s11, v253, 32
	s_nop 1
	v_lshl_add_u64 v[8:9], s[10:11], 0, v[6:7]
	v_add_co_u32_e32 v8, vcc, 0x80000, v8
	s_nop 1
	v_addc_co_u32_e32 v9, vcc, 0, v9, vcc
	global_load_dword v20, v6, s[10:11] nt
	global_load_dword v79, v[8:9], off nt

.LBB0_744:
	s_or_b64 exec, exec, s[0:1]
	v_add_u32_e32 v68, s35, v91
	s_movk_i32 s0, 0x3fff
	v_min_i32_e32 v10, 0x43ff, v68
	v_cmp_lt_i32_e64 s[12:13], s0, v68
	s_and_saveexec_b64 s[0:1], s[12:13]
	s_xor_b64 s[0:1], exec, s[0:1]
	s_cbranch_execz .LBB0_748
	v_add_u32_e32 v1, 0xffffc000, v10
	v_lshrrev_b32_e32 v1, 8, v1
	v_and_b32_e32 v1, 0xfffffe, v1
	v_readlane_b32 s8, v255, 47
	v_mov_b32_e32 v7, v4
	v_readlane_b32 s9, v255, 48
	v_or_b32_e32 v6, s8, v1
	v_lshlrev_b64 v[6:7], 9, v[6:7]
	s_movk_i32 s8, 0x1ff
	v_and_or_b32 v6, v10, s8, v6
	v_lshlrev_b64 v[8:9], 9, v[6:7]
	v_lshl_add_u64 v[8:9], v[40:41], 0, v[8:9]
	global_load_dwordx2 v[74:75], v[8:9], off nt
	v_mov_b32_e32 v1, 0
	s_and_saveexec_b64 s[8:9], s[4:5]
	s_cbranch_execz .LBB0_747
	v_lshlrev_b64 v[6:7], 7, v[6:7]
	v_lshl_add_u64 v[6:7], v[42:43], 0, v[6:7]
	global_load_dword v1, v[6:7], off nt

.LBB0_748:
	s_or_saveexec_b64 s[0:1], s[0:1]
	v_mov_b32_e32 v5, s69
	v_mov_b32_e32 v81, 0
	v_lshlrev_b32_e32 v18, 1, v28
	v_lshlrev_b32_e32 v16, 1, v26
	v_mov_b32_e32 v80, 0
	v_mov_b32_e32 v83, 0
	v_mov_b32_e32 v82, 0
	v_mov_b32_e32 v77, 0
	s_xor_b64 exec, exec, s[0:1]
	s_cbranch_execz .LBB0_754
	v_mov_b64_e32 v[6:7], s[46:47]
	v_mad_i64_i32 v[8:9], s[8:9], v10, s65, v[6:7]
	v_mov_b32_e32 v19, v4
	v_mov_b32_e32 v17, v4
	v_lshl_add_u64 v[6:7], v[8:9], 0, v[18:19]
	v_lshl_add_u64 v[12:13], v[8:9], 0, v[16:17]
	global_load_dwordx2 v[6:7], v[6:7], off nt
	v_mov_b32_e32 v77, 0
	global_load_dword v11, v[12:13], off offset:512 nt
	s_waitcnt vmcnt(0)
	v_mov_b32_e32 v1, 0
	s_and_saveexec_b64 s[8:9], s[4:5]
	s_cbranch_execz .LBB0_751
	v_lshlrev_b32_e32 v12, 1, v24
	v_mov_b32_e32 v13, v4
	v_lshl_add_u64 v[8:9], v[8:9], 0, v[12:13]
	global_load_ushort v1, v[8:9], off offset:768 nt
	s_waitcnt vmcnt(0)
	v_lshlrev_b32_e32 v1, 16, v1
.LBB0_751:
	s_or_b64 exec, exec, s[8:9]
	v_cmp_lt_i32_e32 vcc, s89, v68
	s_and_b64 s[10:11], s[4:5], vcc
	s_and_saveexec_b64 s[8:9], s[10:11]
	s_cbranch_execz .LBB0_753
	v_lshlrev_b32_e32 v5, 5, v10
	s_mov_b32 s10, 0x1ffe0
	v_and_or_b32 v5, v5, s10, v24
	v_readlane_b32 s10, v253, 31
	v_lshlrev_b32_e32 v8, 2, v5
	v_mov_b32_e32 v9, v4
	v_readlane_b32 s11, v253, 32
	s_nop 1
	v_lshl_add_u64 v[12:13], s[10:11], 0, v[8:9]
	v_add_co_u32_e32 v12, vcc, 0x80000, v12
	s_nop 1
	v_addc_co_u32_e32 v13, vcc, 0, v13, vcc
	global_load_dword v5, v8, s[10:11] nt
	global_load_dword v77, v[12:13], off nt

.LBB0_754:
	s_or_b64 exec, exec, s[0:1]
	v_add_u32_e32 v58, s35, v27
	s_movk_i32 s0, 0x3fff
	v_min_i32_e32 v15, 0x43ff, v58
	v_cmp_lt_i32_e64 s[10:11], s0, v58
	s_and_saveexec_b64 s[0:1], s[10:11]
	s_xor_b64 s[0:1], exec, s[0:1]
	s_cbranch_execz .LBB0_758
	v_add_u32_e32 v2, 0xffffc000, v15
	v_lshrrev_b32_e32 v2, 8, v2
	v_and_b32_e32 v2, 0xfffffe, v2
	v_readlane_b32 s8, v255, 47
	v_mov_b32_e32 v7, v4
	v_readlane_b32 s9, v255, 48
	v_or_b32_e32 v6, s8, v2
	v_lshlrev_b64 v[6:7], 9, v[6:7]
	s_movk_i32 s8, 0x1ff
	v_and_or_b32 v6, v15, s8, v6
	v_lshlrev_b64 v[8:9], 9, v[6:7]
	v_lshl_add_u64 v[8:9], v[40:41], 0, v[8:9]
	global_load_dwordx2 v[10:11], v[8:9], off nt
	v_mov_b32_e32 v2, 0
	s_and_saveexec_b64 s[8:9], s[4:5]
	s_cbranch_execz .LBB0_757
	v_lshlrev_b64 v[6:7], 7, v[6:7]
	v_lshl_add_u64 v[6:7], v[42:43], 0, v[6:7]
	global_load_dword v2, v[6:7], off nt

.LBB0_758:
	s_or_saveexec_b64 s[0:1], s[0:1]
	v_mov_b32_e32 v14, s69
	v_mov_b32_e32 v71, 0
	v_mov_b32_e32 v70, 0
	v_mov_b32_e32 v73, 0
	v_mov_b32_e32 v72, 0
	v_mov_b32_e32 v7, 0
	s_xor_b64 exec, exec, s[0:1]
	s_cbranch_execz .LBB0_764
	v_mov_b64_e32 v[6:7], s[46:47]
	s_waitcnt vmcnt(0)
	v_mad_i64_i32 v[10:11], s[8:9], v15, s65, v[6:7]
	v_mov_b32_e32 v19, v4
	v_lshl_add_u64 v[6:7], v[10:11], 0, v[18:19]
	v_mov_b32_e32 v17, v4
	global_load_dwordx2 v[8:9], v[6:7], off nt
	v_lshl_add_u64 v[6:7], v[10:11], 0, v[16:17]
	global_load_dword v6, v[6:7], off offset:512 nt
	v_mov_b32_e32 v7, 0
	v_mov_b32_e32 v2, 0
	s_and_saveexec_b64 s[8:9], s[4:5]
	s_cbranch_execz .LBB0_761
	v_lshlrev_b32_e32 v12, 1, v24
	v_mov_b32_e32 v13, v4
	v_lshl_add_u64 v[10:11], v[10:11], 0, v[12:13]
	global_load_ushort v2, v[10:11], off offset:768 nt
	s_waitcnt vmcnt(0)
	v_lshlrev_b32_e32 v2, 16, v2
.LBB0_761:
	s_or_b64 exec, exec, s[8:9]
	v_cmp_lt_i32_e32 vcc, s89, v58
	s_and_b64 s[16:17], s[4:5], vcc
	s_and_saveexec_b64 s[8:9], s[16:17]
	s_cbranch_execz .LBB0_763
	v_lshlrev_b32_e32 v7, 5, v15
	s_mov_b32 s16, 0x1ffe0
	v_and_or_b32 v7, v7, s16, v24
	v_readlane_b32 s16, v253, 31
	v_lshlrev_b32_e32 v10, 2, v7
	v_mov_b32_e32 v11, v4
	v_readlane_b32 s17, v253, 32
	s_nop 1
	v_lshl_add_u64 v[12:13], s[16:17], 0, v[10:11]
	v_add_co_u32_e32 v12, vcc, 0x80000, v12
	s_nop 1
	v_addc_co_u32_e32 v13, vcc, 0, v13, vcc
	global_load_dword v14, v10, s[16:17] nt
	global_load_dword v7, v[12:13], off nt

.LBB0_764:
	s_or_b64 exec, exec, s[0:1]
	v_add_u32_e32 v56, s35, v29
	s_movk_i32 s0, 0x3fff
	v_min_i32_e32 v6, 0x43ff, v56
	v_cmp_lt_i32_e64 s[8:9], s0, v56
	s_and_saveexec_b64 s[0:1], s[8:9]
	s_xor_b64 s[0:1], exec, s[0:1]
	s_cbranch_execz .LBB0_768
	v_add_u32_e32 v3, 0xffffc000, v6
	v_lshrrev_b32_e32 v3, 8, v3
	v_and_b32_e32 v3, 0xfffffe, v3
	v_readlane_b32 s16, v255, 47
	v_mov_b32_e32 v9, v4
	v_readlane_b32 s17, v255, 48
	v_or_b32_e32 v8, s16, v3
	v_lshlrev_b64 v[8:9], 9, v[8:9]
	s_movk_i32 s16, 0x1ff
	v_and_or_b32 v8, v6, s16, v8
	v_lshlrev_b64 v[12:13], 9, v[8:9]
	v_lshl_add_u64 v[12:13], v[40:41], 0, v[12:13]
	global_load_dwordx2 v[60:61], v[12:13], off nt
	v_mov_b32_e32 v3, 0
	s_and_saveexec_b64 s[70:71], s[4:5]
	s_cbranch_execz .LBB0_767
	v_lshlrev_b64 v[8:9], 7, v[8:9]
	v_lshl_add_u64 v[8:9], v[42:43], 0, v[8:9]
	global_load_dword v3, v[8:9], off nt

.LBB0_768:
	s_or_saveexec_b64 s[0:1], s[0:1]
	v_mov_b32_e32 v15, s69
	v_mov_b32_e32 v63, 0
	v_mov_b32_e32 v62, 0
	v_mov_b32_e32 v65, 0
	v_mov_b32_e32 v64, 0
	v_mov_b32_e32 v21, 0
	s_xor_b64 exec, exec, s[0:1]
	s_cbranch_execz .LBB0_774
	v_mov_b64_e32 v[8:9], s[46:47]
	v_mad_i64_i32 v[12:13], s[16:17], v6, s65, v[8:9]
	v_mov_b32_e32 v19, v4
	v_mov_b32_e32 v17, v4
	v_lshl_add_u64 v[8:9], v[12:13], 0, v[18:19]
	v_lshl_add_u64 v[16:17], v[12:13], 0, v[16:17]
	global_load_dwordx2 v[8:9], v[8:9], off nt
	s_nop 0
	global_load_dword v16, v[16:17], off offset:512 nt
	v_mov_b32_e32 v21, 0
	s_waitcnt vmcnt(0)
	v_mov_b32_e32 v3, 0
	s_and_saveexec_b64 s[70:71], s[4:5]
	s_cbranch_execz .LBB0_771
	v_lshlrev_b32_e32 v18, 1, v24
	v_mov_b32_e32 v19, v4
	v_lshl_add_u64 v[12:13], v[12:13], 0, v[18:19]
	global_load_ushort v3, v[12:13], off offset:768 nt
	s_waitcnt vmcnt(0)
	v_lshlrev_b32_e32 v3, 16, v3
.LBB0_771:
	s_or_b64 exec, exec, s[70:71]
	v_cmp_lt_i32_e32 vcc, s89, v56
	s_and_b64 s[16:17], s[4:5], vcc
	s_and_saveexec_b64 s[70:71], s[16:17]
	s_cbranch_execz .LBB0_773
	v_lshlrev_b32_e32 v6, 5, v6
	s_mov_b32 s16, 0x1ffe0
	v_and_or_b32 v6, v6, s16, v24
	v_readlane_b32 s16, v253, 31
	v_lshlrev_b32_e32 v12, 2, v6
	v_mov_b32_e32 v13, v4
	v_readlane_b32 s17, v253, 32
	s_nop 1
	v_lshl_add_u64 v[18:19], s[16:17], 0, v[12:13]
	v_add_co_u32_e32 v18, vcc, 0x80000, v18
	s_nop 1
	v_addc_co_u32_e32 v19, vcc, 0, v19, vcc
	global_load_dword v15, v12, s[16:17] nt
	global_load_dword v21, v[18:19], off nt

.LBB0_774:
	s_or_b64 exec, exec, s[0:1]
	global_load_dwordx4 v[16:19], v[30:31], off nt
	global_load_dwordx2 v[66:67], v[32:33], off nt
	s_mov_b64 s[70:71], 0
	s_and_saveexec_b64 s[0:1], s[14:15]
	s_xor_b64 s[0:1], exec, s[0:1]
	s_cbranch_execz .LBB0_800
	v_mov_b32_e32 v79, v4
	v_lshlrev_b64 v[8:9], 8, v[78:79]
	s_waitcnt vmcnt(0)
	v_cvt_pk_bf16_f32 v6, v84, v85
	v_lshl_add_u64 v[8:9], v[34:35], 0, v[8:9]
	s_mov_b64 s[14:15], 0
	global_store_dword v[8:9], v6, off
	s_and_saveexec_b64 s[16:17], s[4:5]
	s_xor_b64 s[70:71], exec, s[16:17]
	s_cbranch_execz .LBB0_777
	v_add_u32_e32 v6, 0xffffc000, v78
	v_lshrrev_b32_e32 v6, 9, v6
	v_mul_hi_u32_u24_e32 v9, 0x1200, v6
	v_mul_u32_u24_e32 v6, 0x1200, v6
	s_movk_i32 s16, 0x1ff
	v_and_or_b32 v8, v78, s16, v6
	s_mov_b64 s[16:17], 0x3000
	s_mov_b64 s[14:15], exec
	v_lshl_add_u64 v[8:9], v[8:9], 0, s[16:17]
	v_mov_b32_e32 v6, v0
